# static s_setprio 1 for waves 4-7 around the two dense attention loops (strategy 4)
# baseline (speedup 1.0000x reference)
; #define ALAS __attribute__((address_space(3)))
; template <bool SUB> __device__ __forceinline__ void attn_unit_r2(const AU& u, ALAS unsigned char* lds, float mb2) {
;     ...
;     int tid_o = threadIdx.x; asm volatile("" : "+v"(tid_o));
;     const int tid = tid_o, lane = tid & 63, wid = __builtin_amdgcn_readfirstlane(tid >> 6), r = lane & 31, h = lane >> 5;
;     const int hl = wid / u.wph, qs = u.q0 + 64 * (wid % u.wph);
;     bf16x8 qa[4], qb[4];
;     { const bf16_t* qp = u.Q + (size_t)hl * u.qhs + (size_t)(qs + r) * u.qrs + h * 8;
; #pragma unroll
;       for (int d0 = 0; d0 < 4; ++d0) { qa[d0] = *(const bf16x8*)(qp + d0 * 16); qb[d0] = *(const bf16x8*)(qp + (size_t)32 * u.qrs + d0 * 16); } }
;     const int NT = u.nsub >> 6;
;     const int kr0 = tid >> 3, kc0 = tid & 7;
;     const bf16_t* kg0 = u.K + (size_t)kr0 * u.krs + kc0 * 8; const bf16_t* vg = u.V + (size_t)kr0 * u.vrs + kc0 * 8;
;     const int kl0 = kr0 * KP + kc0 * 16, vl = V_OFF + kr0 * VP + kc0 * 16;
;     f32x16 oa0, oa1, ob0, ob1, negm;
; #pragma unroll
;     for (int i = 0; i < 16; ++i) { oa0[i] = 0.f; oa1[i] = 0.f; ob0[i] = 0.f; ob1[i] = 0.f; negm[i] = SUB ? -mb2 : 0.f; }
;     float la = 0.f, lb = 0.f;
;     u32x4 rk = *(const u32x4*)kg0, rv = *(const u32x4*)vg;
;     *(ALAS u32x4*)(lds + kl0) = rk; *(ALAS u32x4*)(lds + vl) = rv;
;     __syncthreads();
.LBB0_169:
	s_and_b64 vcc, exec, s[52:53]
	s_cbranch_vccz .LBB0_117
	s_and_saveexec_b64 s[20:21], s[38:39]
	s_xor_b64 s[52:53], exec, s[20:21]
	s_cbranch_execz .LBB0_178
	v_mov_b32_e32 v22, v171
	v_mov_b64_e32 v[16:17], s[22:23]
	v_readfirstlane_b32 s2, v22
	s_ashr_i32 s2, s2, 6
	s_lshr_b32 s7, s2, 31
	s_add_i32 s7, s2, s7
	s_ashr_i32 s54, s7, 1
	s_and_b32 s7, s7, 0x3fffffe
	v_ashrrev_i32_e32 v23, 3, v22
	s_movk_i32 s30, 0xc00
	v_lshlrev_b32_e32 v18, 4, v22
	v_mov_b64_e32 v[20:21], s[4:5]
	s_sub_i32 s2, s2, s7
	v_mad_i64_i32 v[16:17], s[20:21], v23, s30, v[16:17]
	v_and_b32_e32 v18, 0x70, v18
	v_mad_i64_i32 v[20:21], s[20:21], v23, s30, v[20:21]
	v_mov_b32_e32 v19, v169
	s_lshl_b32 s2, s2, 6
	v_lshl_add_u64 v[20:21], v[20:21], 0, v[18:19]
	v_lshl_add_u64 v[16:17], v[16:17], 0, v[18:19]
	v_and_b32_e32 v19, 31, v22
	s_ashr_i32 s55, s54, 31
	s_add_i32 s2, s2, s79
	global_load_dwordx4 v[128:131], v[20:21], off
	global_load_dwordx4 v[132:135], v[16:17], off
	s_lshl_b64 s[54:55], s[54:55], 7
	v_or_b32_e32 v16, s2, v19
	s_movk_i32 s7, 0x600
	s_add_u32 s54, s48, s54
	v_mul_lo_u32 v16, v16, s7
	v_bfe_u32 v24, v22, 5, 1
	s_addc_u32 s55, s49, s55
	v_ashrrev_i32_e32 v17, 31, v16
	v_lshlrev_b32_e32 v168, 4, v24
	v_lshl_add_u64 v[16:17], v[16:17], 1, s[54:55]
	v_lshl_add_u64 v[16:17], v[16:17], 0, v[168:169]
	s_mov_b32 s7, 0x18000
	v_add_co_u32_e32 v20, vcc, s7, v16
	v_bfe_u32 v25, v22, 2, 2
	s_nop 0
	v_addc_co_u32_e32 v21, vcc, 0, v17, vcc
	global_load_dwordx4 v[136:139], v[16:17], off
	global_load_dwordx4 v[140:143], v[16:17], off offset:32
	global_load_dwordx4 v[144:147], v[16:17], off offset:64
	global_load_dwordx4 v[148:151], v[16:17], off offset:96
	global_load_dwordx4 v[152:155], v[20:21], off
	global_load_dwordx4 v[156:159], v[20:21], off offset:32
	global_load_dwordx4 v[160:163], v[20:21], off offset:64
	global_load_dwordx4 v[164:167], v[20:21], off offset:96
	v_lshlrev_b32_e32 v16, 1, v22
	v_lshlrev_b32_e32 v17, 3, v22
	s_movk_i32 s7, 0x90
	v_mul_u32_u24_e32 v19, 0x90, v19
	v_lshl_or_b32 v21, v24, 2, v25
	v_and_b32_e32 v22, 32, v16
	v_and_b32_e32 v24, 24, v17
	v_mad_i64_i32 v[16:17], s[54:55], v23, s30, 0
	v_mul_lo_u32 v20, v23, s7
	v_add3_u32 v168, 0, v19, v168
	v_mad_u32_u24 v19, v21, s7, 0
	v_or_b32_e32 v16, v16, v18
	v_mov_b32_e32 v48, 0
	v_add3_u32 v220, v18, v20, 0
	v_add3_u32 v221, v19, v22, v24
	v_lshl_add_u64 v[18:19], s[4:5], 0, v[16:17]
	v_lshl_add_u64 v[16:17], s[22:23], 0, v[16:17]
	s_mov_b32 s21, 0
	v_mov_b32_e32 v49, v48
	v_mov_b32_e32 v50, v48
	v_mov_b32_e32 v51, v48
	v_mov_b32_e32 v52, v48
	v_mov_b32_e32 v53, v48
	v_mov_b32_e32 v54, v48
	v_mov_b32_e32 v55, v48
	v_mov_b32_e32 v56, v48
	v_mov_b32_e32 v57, v48
	v_mov_b32_e32 v58, v48
	v_lshl_add_u64 v[174:175], v[18:19], 0, s[12:13]
	v_lshl_add_u64 v[176:177], v[16:17], 0, s[12:13]
	s_lshr_b32 s7, s78, 6
	v_mov_b32_e32 v59, v48
	v_mov_b32_e32 v60, v48
	v_mov_b32_e32 v61, v48
	v_mov_b32_e32 v62, v48
	v_mov_b32_e32 v63, v48
	v_mov_b32_e32 v64, v48
	v_mov_b32_e32 v65, v48
	v_mov_b32_e32 v66, v48
	v_mov_b32_e32 v67, v48
	v_mov_b32_e32 v68, v48
	v_mov_b32_e32 v69, v48
	v_mov_b32_e32 v70, v48
	v_mov_b32_e32 v71, v48
	v_mov_b32_e32 v72, v48
	v_mov_b32_e32 v73, v48
	v_mov_b32_e32 v74, v48
	v_mov_b32_e32 v75, v48
	v_mov_b32_e32 v76, v48
	v_mov_b32_e32 v77, v48
	v_mov_b32_e32 v78, v48
	v_mov_b32_e32 v79, v48
	v_mov_b32_e32 v16, v48
	v_mov_b32_e32 v17, v48
	v_mov_b32_e32 v18, v48
	v_mov_b32_e32 v19, v48
	v_mov_b32_e32 v20, v48
	v_mov_b32_e32 v21, v48
	v_mov_b32_e32 v22, v48
	v_mov_b32_e32 v23, v48
	v_mov_b32_e32 v24, v48
	v_mov_b32_e32 v25, v48
	v_mov_b32_e32 v26, v48
	v_mov_b32_e32 v27, v48
	v_mov_b32_e32 v28, v48
	v_mov_b32_e32 v29, v48
	v_mov_b32_e32 v30, v48
	v_mov_b32_e32 v31, v48
	v_mov_b32_e32 v32, v48
	v_mov_b32_e32 v33, v48
	v_mov_b32_e32 v34, v48
	v_mov_b32_e32 v35, v48
	v_mov_b32_e32 v36, v48
	v_mov_b32_e32 v37, v48
	v_mov_b32_e32 v38, v48
	v_mov_b32_e32 v39, v48
	v_mov_b32_e32 v40, v48
	v_mov_b32_e32 v41, v48
	v_mov_b32_e32 v42, v48
	v_mov_b32_e32 v43, v48
	v_mov_b32_e32 v44, v48
	v_mov_b32_e32 v45, v48
	v_mov_b32_e32 v46, v48
	v_mov_b32_e32 v47, v48
	v_mov_b32_e32 v172, v48
	v_mov_b32_e32 v173, v48
	v_mov_b32_e32 v242, v48
	v_mov_b32_e32 v243, v48
	v_mov_b32_e32 v112, v48
	v_mov_b32_e32 v113, v48
	v_mov_b32_e32 v114, v48
	v_mov_b32_e32 v115, v48
	v_mov_b32_e32 v116, v48
	v_mov_b32_e32 v117, v48
	v_mov_b32_e32 v118, v48
	v_mov_b32_e32 v119, v48
	v_mov_b32_e32 v120, v48
	v_mov_b32_e32 v121, v48
	v_mov_b32_e32 v122, v48
	v_mov_b32_e32 v123, v48
	v_mov_b32_e32 v124, v48
	v_mov_b32_e32 v125, v48
	v_mov_b32_e32 v126, v48
	v_mov_b32_e32 v127, v48
	v_mov_b32_e32 v0, v48
	v_mov_b32_e32 v1, v48
	v_mov_b32_e32 v2, v48
	v_mov_b32_e32 v3, v48
	v_mov_b32_e32 v4, v48
	v_mov_b32_e32 v5, v48
	v_mov_b32_e32 v6, v48
	v_mov_b32_e32 v7, v48
	v_mov_b32_e32 v8, v48
	v_mov_b32_e32 v9, v48
	v_mov_b32_e32 v10, v48
	v_mov_b32_e32 v11, v48
	v_mov_b32_e32 v12, v48
	v_mov_b32_e32 v13, v48
	v_mov_b32_e32 v14, v48
	v_mov_b32_e32 v15, v48
	v_mov_b32_e32 v80, v48
	v_mov_b32_e32 v81, v48
	v_mov_b32_e32 v82, v48
	v_mov_b32_e32 v83, v48
	v_mov_b32_e32 v84, v48
	v_mov_b32_e32 v85, v48
	v_mov_b32_e32 v86, v48
	v_mov_b32_e32 v87, v48
	v_mov_b32_e32 v88, v48
	v_mov_b32_e32 v89, v48
	v_mov_b32_e32 v90, v48
	v_mov_b32_e32 v91, v48
	v_mov_b32_e32 v92, v48
	v_mov_b32_e32 v93, v48
	v_mov_b32_e32 v94, v48
	v_mov_b32_e32 v95, v48
	v_mov_b32_e32 v96, v48
	v_mov_b32_e32 v97, v48
	v_mov_b32_e32 v98, v48
	v_mov_b32_e32 v99, v48
	v_mov_b32_e32 v100, v48
	v_mov_b32_e32 v101, v48
	v_mov_b32_e32 v102, v48
	v_mov_b32_e32 v103, v48
	v_mov_b32_e32 v104, v48
	v_mov_b32_e32 v105, v48
	v_mov_b32_e32 v106, v48
	v_mov_b32_e32 v107, v48
	v_mov_b32_e32 v108, v48
	v_mov_b32_e32 v109, v48
	v_mov_b32_e32 v110, v48
	v_mov_b32_e32 v111, v48
	v_mov_b32_e32 v178, v48
	v_mov_b32_e32 v179, v48
	v_mov_b32_e32 v180, v48
	v_mov_b32_e32 v181, v48
	v_mov_b32_e32 v182, v48
	v_mov_b32_e32 v183, v48
	v_mov_b32_e32 v184, v48
	v_mov_b32_e32 v185, v48
	v_mov_b32_e32 v186, v48
	v_mov_b32_e32 v187, v48
	v_mov_b32_e32 v188, v48
	v_mov_b32_e32 v189, v48
	v_mov_b32_e32 v190, v48
	v_mov_b32_e32 v191, v48
	v_mov_b32_e32 v192, v48
	v_mov_b32_e32 v193, v48
	v_mov_b32_e32 v194, v48
	v_mov_b32_e32 v195, v48
	v_mov_b32_e32 v196, v48
	v_mov_b32_e32 v197, v48
	v_mov_b32_e32 v210, v48
	v_mov_b32_e32 v211, v48
	v_mov_b32_e32 v212, v48
	v_mov_b32_e32 v213, v48
	v_mov_b32_e32 v238, v48
	v_mov_b32_e32 v239, v48
	v_mov_b32_e32 v240, v48
	v_mov_b32_e32 v241, v48
	v_mov_b32_e32 v248, v48
	v_mov_b32_e32 v249, v48
	v_mov_b32_e32 v250, v48
	v_mov_b32_e32 v251, v48
	s_waitcnt vmcnt(9)
	ds_write_b128 v220, v[128:131]
	s_waitcnt vmcnt(0)
	ds_write_b128 v220, v[132:135] offset:18432
	s_waitcnt lgkmcnt(0)
	v_readfirstlane_b32 s56, v171
	s_nop 3
	s_lshr_b32 s56, s56, 6
	s_cmp_ge_u32 s56, 4
	s_cbranch_scc0 .Lr2n_noprio
	s_setprio 1
.Lr2n_noprio:
	s_barrier
	s_branch .Lr2n_topA

; #define ALAS __attribute__((address_space(3)))
; __device__ __forceinline__ s16x4 vtr(const ALAS unsigned char* p) { return __builtin_bit_cast(s16x4, __builtin_amdgcn_ds_read_tr16_b64_v4i16((ALAS s16x4*)p)); }
; #define AMFMA(a, b, c) __builtin_amdgcn_mfma_f32_32x32x16_bf16((a), (b), (c), 0, 0, 0)
; template <bool SUB> __device__ __forceinline__ void attn_unit_r2(const AU& u, ALAS unsigned char* lds, float mb2) {
;     ...
;             R2_SOFT(Sa0, Sa1, paa, la);
;             R2_SOFT(Sb0, Sb1, pab, lb);
;     ...
; #pragma unroll
;             for (int ks = 0; ks < 4; ++ks) {
;                 const s16x4 lo0 = vtr(vb + ks * 16 * VP), hi0 = vtr(vb + (ks * 16 + 8) * VP), lo1 = vtr(vb + ks * 16 * VP + 64), hi1 = vtr(vb + (ks * 16 + 8) * VP + 64);
;                 const bf16x8 vf0 = __builtin_shufflevector(lo0, hi0, 0, 1, 2, 3, 4, 5, 6, 7), vf1 = __builtin_shufflevector(lo1, hi1, 0, 1, 2, 3, 4, 5, 6, 7);
;                 oa0 = AMFMA(paa[ks], vf0, oa0); oa1 = AMFMA(paa[ks], vf1, oa1); ob0 = AMFMA(pab[ks], vf0, ob0); ob1 = AMFMA(pab[ks], vf1, ob1);
;             }
;         }
;         if (t + 1 < NT) { *(ALAS u32x4*)(lds + (cur ^ 1) * KBUF + kl0) = rk; *(ALAS u32x4*)(lds + (cur ^ 1) * VBUF + vl) = rv; }
;         __syncthreads();
;     }
;     la += __shfl_xor(la, 32); lb += __shfl_xor(lb, 32);
.Lr2n_nowriteB:
	s_cmp_lt_u32 s20, s7
	s_mov_b32 s21, s20
	s_waitcnt lgkmcnt(0)
	s_barrier
	s_cbranch_scc1 .Lr2n_topA
	s_setprio 0
	v_mfma_f32_32x32x16_bf16 v[48:63], v[178:181], v[238:241], v[48:63]
	v_add_f32_e32 v172, v96, v172
	v_add_f32_e32 v173, v80, v173
	v_add_f32_e32 v172, v97, v172
	v_add_f32_e32 v173, v81, v173
	v_mfma_f32_32x32x16_bf16 v[64:79], v[178:181], v[248:251], v[64:79]
	v_add_f32_e32 v172, v98, v172
	v_add_f32_e32 v173, v82, v173
	v_add_f32_e32 v172, v99, v172
	v_add_f32_e32 v173, v83, v173
	v_mfma_f32_32x32x16_bf16 v[16:31], v[182:185], v[238:241], v[16:31]
	v_add_f32_e32 v172, v100, v172
	v_add_f32_e32 v173, v84, v173
	v_add_f32_e32 v172, v101, v172
	v_add_f32_e32 v173, v85, v173
	v_mfma_f32_32x32x16_bf16 v[32:47], v[182:185], v[248:251], v[32:47]
	v_add_f32_e32 v172, v102, v172
	v_add_f32_e32 v173, v86, v173
	v_add_f32_e32 v172, v103, v172
	v_add_f32_e32 v173, v87, v173
	v_mfma_f32_32x32x16_bf16 v[48:63], v[186:189], v[194:197], v[48:63]
	v_add_f32_e32 v172, v104, v172
	v_add_f32_e32 v173, v88, v173
	v_add_f32_e32 v172, v105, v172
	v_add_f32_e32 v173, v89, v173
	v_mfma_f32_32x32x16_bf16 v[64:79], v[186:189], v[210:213], v[64:79]
	v_add_f32_e32 v172, v106, v172
	v_add_f32_e32 v173, v90, v173
	v_add_f32_e32 v172, v107, v172
	v_add_f32_e32 v173, v91, v173
	v_mfma_f32_32x32x16_bf16 v[16:31], v[190:193], v[194:197], v[16:31]
	v_add_f32_e32 v172, v108, v172
	v_add_f32_e32 v173, v92, v173
	v_add_f32_e32 v172, v109, v172
	v_add_f32_e32 v173, v93, v173
	v_mfma_f32_32x32x16_bf16 v[32:47], v[190:193], v[210:213], v[32:47]
	v_add_f32_e32 v172, v110, v172
	v_add_f32_e32 v173, v94, v173
	v_add_f32_e32 v172, v111, v172
	v_add_f32_e32 v173, v95, v173
	v_add_f32_e32 v242, v112, v242
	v_add_f32_e32 v243, v0, v243
	v_add_f32_e32 v242, v113, v242
	v_add_f32_e32 v243, v1, v243
	v_add_f32_e32 v242, v114, v242
	v_add_f32_e32 v243, v2, v243
	v_add_f32_e32 v242, v115, v242
	v_add_f32_e32 v243, v3, v243
	v_add_f32_e32 v242, v116, v242
	v_add_f32_e32 v243, v4, v243
	v_add_f32_e32 v242, v117, v242
	v_add_f32_e32 v243, v5, v243
	v_add_f32_e32 v242, v118, v242
	v_add_f32_e32 v243, v6, v243
	v_add_f32_e32 v242, v119, v242
	v_add_f32_e32 v243, v7, v243
	v_add_f32_e32 v242, v120, v242
	v_add_f32_e32 v243, v8, v243
	v_add_f32_e32 v242, v121, v242
	v_add_f32_e32 v243, v9, v243
	v_add_f32_e32 v242, v122, v242
	v_add_f32_e32 v243, v10, v243
	v_add_f32_e32 v242, v123, v242
	v_add_f32_e32 v243, v11, v243
	v_add_f32_e32 v242, v124, v242
	v_add_f32_e32 v243, v12, v243
	v_add_f32_e32 v242, v125, v242
	v_add_f32_e32 v243, v13, v243
	v_add_f32_e32 v242, v126, v242
	v_add_f32_e32 v243, v14, v243
	v_add_f32_e32 v242, v127, v242
	v_add_f32_e32 v243, v15, v243
	v_add_f32_e32 v172, v172, v242
	v_add_f32_e32 v173, v173, v243
	v_xor_b32_e32 v0, 0x80000000, v219
	v_mov_b32_e32 v1, v0
	v_mov_b32_e32 v2, v0
	v_mov_b32_e32 v3, v0
	v_mov_b32_e32 v4, v0
	v_mov_b32_e32 v5, v0
	v_mov_b32_e32 v6, v0
	v_mov_b32_e32 v7, v0
	v_mov_b32_e32 v8, v0
	v_mov_b32_e32 v9, v0
	v_mov_b32_e32 v10, v0
	v_mov_b32_e32 v11, v0
	v_mov_b32_e32 v12, v0
	v_mov_b32_e32 v13, v0
	v_mov_b32_e32 v14, v0
	v_mov_b32_e32 v15, v0

; #define ALAS __attribute__((address_space(3)))
; template <bool SUB> __device__ __forceinline__ void attn_unit_r2b(const AU& u, ALAS unsigned char* lds, float mb2) {
;     ...
;     int tid_o = threadIdx.x; asm volatile("" : "+v"(tid_o));
;     const int tid = tid_o, lane = tid & 63, wid = __builtin_amdgcn_readfirstlane(tid >> 6), r = lane & 31, h = lane >> 5;
;     const int qs = u.q0 + 64 * wid;
;     bf16x8 qa[6];
;     ALAS unsigned char* qbl = lds + QB_OFF + wid * 6144 + lane * 16;
;     { const bf16_t* qp = u.Q + (size_t)(qs + r) * u.qrs + h * 8;
; #pragma unroll
;       for (int d0 = 0; d0 < 6; ++d0) { qa[d0] = *(const bf16x8*)(qp + d0 * 16); const bf16x8 t_ = *(const bf16x8*)(qp + (size_t)32 * u.qrs + d0 * 16); *(ALAS bf16x8*)(qbl + d0 * 1024) = t_; } }
;     const int NT = u.nsub >> 6;
;     const int kr0 = tid / 12, kc0 = tid - kr0 * 12, c1 = tid + 512, kr1 = c1 / 12, kc1 = c1 - kr1 * 12, vr_ = tid >> 3, vc_ = tid & 7;
;     const bool k2 = tid < 256;
;     const bf16_t* kg0 = u.K + (size_t)kr0 * u.krs + kc0 * 8; const bf16_t* kg1 = u.K + (size_t)kr1 * u.krs + kc1 * 8; const bf16_t* vg = u.V + (size_t)vr_ * u.vrs + vc_ * 8;
;     const int kl0 = kr0 * KP + kc0 * 16, kl1 = kr1 * KP + kc1 * 16, vl = V_OFF + vr_ * VP + vc_ * 16;
;     f32x16 oa0, oa1, ob0, ob1;
; #pragma unroll
;     for (int i = 0; i < 16; ++i) { oa0[i] = 0.f; oa1[i] = 0.f; ob0[i] = 0.f; ob1[i] = 0.f; }
;     float la = 0.f, lb = 0.f;
;     u32x4 rk0 = *(const u32x4*)kg0, rk1 = (u32x4){0u, 0u, 0u, 0u}, rv = *(const u32x4*)vg;
;     if (k2) rk1 = *(const u32x4*)kg1;
;     *(ALAS u32x4*)(lds + kl0) = rk0; if (k2) *(ALAS u32x4*)(lds + kl1) = rk1; *(ALAS u32x4*)(lds + vl) = rv;
;     __syncthreads();
.LBB0_277:
	s_or_b64 exec, exec, s[56:57]
	s_movk_i32 s34, 0xc00
	v_mad_i64_i32 v[6:7], s[56:57], v19, s34, 0
	s_movk_i32 s34, 0x90
	v_mul_lo_u32 v8, v12, s34
	v_add3_u32 v196, 0, v8, v14
	v_mul_u32_u24_e32 v8, 0xd0, v18
	v_add3_u32 v168, 0, v8, v168
	v_bfe_u32 v8, v0, 2, 2
	v_lshl_or_b32 v1, v1, 2, v8
	v_lshlrev_b32_e32 v8, 1, v0
	v_lshlrev_b32_e32 v0, 3, v0
	v_mad_u32_u24 v1, v1, s34, 0
	v_and_b32_e32 v8, 32, v8
	v_and_b32_e32 v0, 24, v0
	v_readlane_b32 s34, v254, 45
	v_add3_u32 v197, v1, v8, v0
	v_lshl_add_u64 v[0:1], s[42:43], 0, v[16:17]
	v_mov_b32_e32 v15, v169
	s_add_u32 s56, s34, s44
	v_readlane_b32 s34, v254, 46
	v_lshl_add_u64 v[0:1], v[0:1], 0, v[14:15]
	s_addc_u32 s57, s34, s45
	v_lshl_add_u64 v[166:167], s[56:57], 0, v[0:1]
	s_add_u32 s56, s22, s7
	s_addc_u32 s57, s23, s2
	v_lshl_add_u64 v[0:1], s[56:57], 0, v[6:7]
	v_readlane_b32 s34, v254, 47
	v_lshl_add_u64 v[0:1], v[4:5], 1, v[0:1]
	v_readlane_b32 s35, v254, 48
	v_mov_b32_e32 v32, 0
	s_mov_b32 s62, 0
	v_lshl_add_u64 v[172:173], s[34:35], 0, v[0:1]
	v_lshl_add_u64 v[0:1], s[56:57], 0, v[10:11]
	v_lshl_add_u64 v[0:1], v[2:3], 1, v[0:1]
	v_lshl_add_u64 v[174:175], s[34:35], 0, v[0:1]
	v_mov_b32_e32 v33, v32
	v_mov_b32_e32 v34, v32
	v_mov_b32_e32 v35, v32
	v_mov_b32_e32 v36, v32
	v_mov_b32_e32 v37, v32
	v_mov_b32_e32 v38, v32
	v_mov_b32_e32 v39, v32
	v_mov_b32_e32 v40, v32
	v_mov_b32_e32 v41, v32
	v_mov_b32_e32 v42, v32
	v_mov_b32_e32 v43, v32
	v_mov_b32_e32 v44, v32
	v_mov_b32_e32 v45, v32
	v_mov_b32_e32 v46, v32
	v_mov_b32_e32 v47, v32
	v_mov_b32_e32 v48, v32
	v_mov_b32_e32 v49, v32
	v_mov_b32_e32 v50, v32
	v_mov_b32_e32 v51, v32
	v_mov_b32_e32 v52, v32
	v_mov_b32_e32 v53, v32
	v_mov_b32_e32 v54, v32
	v_mov_b32_e32 v55, v32
	v_mov_b32_e32 v56, v32
	v_mov_b32_e32 v57, v32
	v_mov_b32_e32 v58, v32
	v_mov_b32_e32 v59, v32
	v_mov_b32_e32 v60, v32
	v_mov_b32_e32 v61, v32
	v_mov_b32_e32 v62, v32
	v_mov_b32_e32 v63, v32
	v_mov_b32_e32 v0, v32
	v_mov_b32_e32 v1, v32
	v_mov_b32_e32 v2, v32
	v_mov_b32_e32 v3, v32
	v_mov_b32_e32 v4, v32
	v_mov_b32_e32 v5, v32
	v_mov_b32_e32 v6, v32
	v_mov_b32_e32 v7, v32
	v_mov_b32_e32 v8, v32
	v_mov_b32_e32 v9, v32
	v_mov_b32_e32 v10, v32
	v_mov_b32_e32 v11, v32
	v_mov_b32_e32 v12, v32
	v_mov_b32_e32 v13, v32
	v_mov_b32_e32 v14, v32
	v_mov_b32_e32 v15, v32
	v_mov_b32_e32 v16, v32
	v_mov_b32_e32 v17, v32
	v_mov_b32_e32 v18, v32
	v_mov_b32_e32 v19, v32
	v_mov_b32_e32 v20, v32
	v_mov_b32_e32 v21, v32
	v_mov_b32_e32 v22, v32
	v_mov_b32_e32 v23, v32
	v_mov_b32_e32 v24, v32
	v_mov_b32_e32 v25, v32
	v_mov_b32_e32 v26, v32
	v_mov_b32_e32 v27, v32
	v_mov_b32_e32 v28, v32
	v_mov_b32_e32 v29, v32
	v_mov_b32_e32 v30, v32
	v_mov_b32_e32 v31, v32
	v_mov_b32_e32 v164, v32
	v_mov_b32_e32 v165, v32
	s_waitcnt vmcnt(0)
	ds_write_b128 v196, v[160:163] offset:26624
	v_mov_b32_e32 v242, v32
	v_mov_b32_e32 v243, v32
	v_mov_b32_e32 v112, v32
	v_mov_b32_e32 v113, v32
	v_mov_b32_e32 v114, v32
	v_mov_b32_e32 v115, v32
	v_mov_b32_e32 v116, v32
	v_mov_b32_e32 v117, v32
	v_mov_b32_e32 v118, v32
	v_mov_b32_e32 v119, v32
	v_mov_b32_e32 v120, v32
	v_mov_b32_e32 v121, v32
	v_mov_b32_e32 v122, v32
	v_mov_b32_e32 v123, v32
	v_mov_b32_e32 v124, v32
	v_mov_b32_e32 v125, v32
	v_mov_b32_e32 v126, v32
	v_mov_b32_e32 v127, v32
	v_mov_b32_e32 v80, v32
	v_mov_b32_e32 v81, v32
	v_mov_b32_e32 v82, v32
	v_mov_b32_e32 v83, v32
	v_mov_b32_e32 v84, v32
	v_mov_b32_e32 v85, v32
	v_mov_b32_e32 v86, v32
	v_mov_b32_e32 v87, v32
	v_mov_b32_e32 v88, v32
	v_mov_b32_e32 v89, v32
	v_mov_b32_e32 v90, v32
	v_mov_b32_e32 v91, v32
	v_mov_b32_e32 v92, v32
	v_mov_b32_e32 v93, v32
	v_mov_b32_e32 v94, v32
	v_mov_b32_e32 v95, v32
	s_waitcnt lgkmcnt(0)
	v_readfirstlane_b32 s34, v171
	s_nop 3
	s_lshr_b32 s34, s34, 6
	s_cmp_ge_u32 s34, 4
	s_cbranch_scc0 .Lr2b_noprio
	s_setprio 1

; #define ALAS __attribute__((address_space(3)))
; __device__ __forceinline__ s16x4 vtr(const ALAS unsigned char* p) { return __builtin_bit_cast(s16x4, __builtin_amdgcn_ds_read_tr16_b64_v4i16((ALAS s16x4*)p)); }
; #define AMFMA(a, b, c) __builtin_amdgcn_mfma_f32_32x32x16_bf16((a), (b), (c), 0, 0, 0)
; template <bool SUB> __device__ __forceinline__ void attn_unit_r2b(const AU& u, ALAS unsigned char* lds, float mb2) {
;     ...
;             R2B_SOFT(Sa0, Sa1, paa, la);
;             __builtin_amdgcn_sched_barrier(0);
;             R2B_SOFT(Sb0, Sb1, pab, lb);
;     ...
; #pragma unroll
;             for (int ks = 0; ks < 4; ++ks) {
;                 const s16x4 lo0 = vtr(vb + ks * 16 * VP), hi0 = vtr(vb + (ks * 16 + 8) * VP), lo1 = vtr(vb + ks * 16 * VP + 64), hi1 = vtr(vb + (ks * 16 + 8) * VP + 64);
;                 const bf16x8 vf0 = __builtin_shufflevector(lo0, hi0, 0, 1, 2, 3, 4, 5, 6, 7), vf1 = __builtin_shufflevector(lo1, hi1, 0, 1, 2, 3, 4, 5, 6, 7);
;                 oa0 = AMFMA(paa[ks], vf0, oa0); oa1 = AMFMA(paa[ks], vf1, oa1); ob0 = AMFMA(pab[ks], vf0, ob0); ob1 = AMFMA(pab[ks], vf1, ob1);
;             }
;         }
;         if (t + 1 < NT) { *(ALAS u32x4*)(lds + (cur ^ 1) * KBUF + kl0) = rk0; if (k2) *(ALAS u32x4*)(lds + (cur ^ 1) * KBUF + kl1) = rk1; *(ALAS u32x4*)(lds + (cur ^ 1) * VBUF + vl) = rv; }
;         __syncthreads();
;     }
;     la += __shfl_xor(la, 32); lb += __shfl_xor(lb, 32);
.Lr2b_nowriteB:
	v_mfma_f32_32x32x16_bf16 v[0:15], v[180:183], v[184:187], v[0:15]
	v_mfma_f32_32x32x16_bf16 v[16:31], v[180:183], v[248:251], v[16:31]
	s_cmp_lt_u32 s61, s28
	s_mov_b32 s62, s61
	s_waitcnt lgkmcnt(0)
	s_barrier
	s_cbranch_scc1 .Lr2b_topA
	s_setprio 0
	v_add_f32_e32 v242, v112, v242
	v_add_f32_e32 v243, v80, v243
	v_add_f32_e32 v242, v113, v242
	v_add_f32_e32 v243, v81, v243
	v_add_f32_e32 v242, v114, v242
	v_add_f32_e32 v243, v82, v243
	v_add_f32_e32 v242, v115, v242
	v_add_f32_e32 v243, v83, v243
	v_add_f32_e32 v242, v116, v242
	v_add_f32_e32 v243, v84, v243
	v_add_f32_e32 v242, v117, v242
	v_add_f32_e32 v243, v85, v243
	v_add_f32_e32 v242, v118, v242
	v_add_f32_e32 v243, v86, v243
	v_add_f32_e32 v242, v119, v242
	v_add_f32_e32 v243, v87, v243
	v_add_f32_e32 v242, v120, v242
	v_add_f32_e32 v243, v88, v243
	v_add_f32_e32 v242, v121, v242
	v_add_f32_e32 v243, v89, v243
	v_add_f32_e32 v242, v122, v242
	v_add_f32_e32 v243, v90, v243
	v_add_f32_e32 v242, v123, v242
	v_add_f32_e32 v243, v91, v243
	v_add_f32_e32 v242, v124, v242
	v_add_f32_e32 v243, v92, v243
	v_add_f32_e32 v242, v125, v242
	v_add_f32_e32 v243, v93, v243
	v_add_f32_e32 v242, v126, v242
	v_add_f32_e32 v243, v94, v243
	v_add_f32_e32 v242, v127, v242
	v_add_f32_e32 v243, v95, v243
	v_add_f32_e32 v164, v164, v242
	v_add_f32_e32 v165, v165, v243
	v_mov_b32_e32 v244, v169
	v_mov_b32_e32 v245, v169
	v_mov_b32_e32 v246, v169
	v_mov_b32_e32 v247, v169
